# GQA attention K loop: cross-half permute index and LDS read base hoisted out of the loop (7 VALU per tile); on top of v49
# baseline (speedup 1.0000x reference)
; DI float fexp2(float x) { return __builtin_amdgcn_exp2f(x); }
; template <int DK, int DV, int MODE, int QB, bool PACK = false>
; DI void attn_item(const AttArgs& a, int q0, int t_lo, int t_hi) {
;     ...
;         const float mc = -m[qb] * cexp;
;         const f32x2 c2 = {cexp, cexp}, mc2 = {mc, mc};
;         f32x2 ps2 = {0.f, 0.f};
; #pragma unroll
;         for (int kb = 0; kb < 2; ++kb)
; #pragma unroll
;           for (int i = 0; i < 16; i += 2) {
;             const f32x2 sv = {s[qb][kb][i], s[qb][kb][i + 1]};
;             const f32x2 e2 = sv * c2 + mc2;
;             f32x2 pv = {fexp2(e2[0]), fexp2(e2[1])};
;             if constexpr (MODE == 1 || MODE == 2) {
;               pv[0] = (sv[0] > -1e29f) ? pv[0] : 0.f;
;               pv[1] = (sv[1] > -1e29f) ? pv[1] : 0.f;
;             }
;             s[qb][kb][i] = pv[0];
;             s[qb][kb][i + 1] = pv[1];
;             ps2 += pv;
;           }
;         lsum[qb] += ps2[0] + ps2[1];
;       }
; #pragma unroll
;       for (int qb = 0; qb < QB; ++qb)
; #pragma unroll
;         for (int kb = 0; kb < 2; ++kb)
; #pragma unroll
;           for (int st = 0; st < 2; ++st) {
;             u32x4 pk;
;             pk[0] = pack2(s[qb][kb][8 * st + 0], s[qb][kb][8 * st + 1]);
;             pk[1] = pack2(s[qb][kb][8 * st + 2], s[qb][kb][8 * st + 3]);
;             pk[2] = pack2(s[qb][kb][8 * st + 4], s[qb][kb][8 * st + 5]);
;             pk[3] = pack2(s[qb][kb][8 * st + 6], s[qb][kb][8 * st + 7]);
;             const bf16x8 pf = __builtin_bit_cast(bf16x8, pk);
;             const unsigned char* vrow = Vb + (kb * 32 + 16 * st + 4 * h + vq) * VST + (16 * vblk + 4 * vp) * 2;
; #pragma unroll
;             for (int d = 0; d < NDB; ++d) {
;               s16x4 lo = __builtin_amdgcn_ds_read_tr16_b64_v4i16((s16x4 __attribute__((address_space(3)))*)(vrow + d * 64));
;               s16x4 hi = __builtin_amdgcn_ds_read_tr16_b64_v4i16((s16x4 __attribute__((address_space(3)))*)(vrow + 8 * VST + d * 64));
;               const bf16x8 vf = __builtin_shufflevector(lo, hi, 0, 1, 2, 3, 4, 5, 6, 7);
.LBB0_633:
	v_mov_b32_e32 v1, v0
	v_pk_fma_f32 v[4:5], v[128:129], s[16:17], v[0:1] op_sel_hi:[1,0,1]
	v_pk_fma_f32 v[6:7], v[130:131], s[16:17], v[0:1] op_sel_hi:[1,0,1]
	v_exp_f32_e32 v12, v4
	v_exp_f32_e32 v13, v5
	v_exp_f32_e32 v14, v6
	v_exp_f32_e32 v15, v7
	v_pk_fma_f32 v[6:7], v[132:133], s[16:17], v[0:1] op_sel_hi:[1,0,1]
	v_pk_add_f32 v[4:5], v[12:13], 0 op_sel_hi:[1,0]
	v_exp_f32_e32 v150, v6
	v_exp_f32_e32 v151, v7
	v_pk_fma_f32 v[6:7], v[134:135], s[16:17], v[0:1] op_sel_hi:[1,0,1]
	v_pk_fma_f32 v[8:9], v[138:139], s[16:17], v[0:1] op_sel_hi:[1,0,1]
	v_exp_f32_e32 v152, v6
	v_exp_f32_e32 v153, v7
	v_pk_fma_f32 v[6:7], v[136:137], s[16:17], v[0:1] op_sel_hi:[1,0,1]
	v_pk_add_f32 v[4:5], v[14:15], v[4:5]
	v_exp_f32_e32 v6, v6
	v_exp_f32_e32 v7, v7
	v_exp_f32_e32 v10, v8
	v_exp_f32_e32 v11, v9
	v_pk_fma_f32 v[8:9], v[140:141], s[16:17], v[0:1] op_sel_hi:[1,0,1]
	v_pk_add_f32 v[4:5], v[150:151], v[4:5]
	v_exp_f32_e32 v136, v8
	v_exp_f32_e32 v137, v9
	v_pk_fma_f32 v[8:9], v[142:143], s[16:17], v[0:1] op_sel_hi:[1,0,1]
	v_pk_add_f32 v[4:5], v[152:153], v[4:5]
	v_exp_f32_e32 v140, v8
	v_exp_f32_e32 v141, v9
	v_pk_add_f32 v[4:5], v[6:7], v[4:5]
	v_mov_b32_e32 v191, v190
	v_pk_add_f32 v[4:5], v[10:11], v[4:5]
	v_pk_fma_f32 v[80:81], v[80:81], s[16:17], v[190:191] op_sel_hi:[1,0,1]
	v_pk_add_f32 v[4:5], v[136:137], v[4:5]
	s_add_u32 s0, s0, s12
	v_pk_add_f32 v[8:9], v[140:141], v[4:5]
	v_pk_fma_f32 v[4:5], v[112:113], s[16:17], v[0:1] op_sel_hi:[1,0,1]
	s_addc_u32 s1, s1, 0
	v_exp_f32_e32 v4, v4
	v_exp_f32_e32 v5, v5
	s_lshl_b32 s2, s8, 1
	s_add_u32 s0, s0, s2
	s_addc_u32 s1, s1, 0
	v_pk_add_f32 v[112:113], v[4:5], v[8:9]
	v_pk_fma_f32 v[8:9], v[114:115], s[16:17], v[0:1] op_sel_hi:[1,0,1]
	v_pk_fma_f32 v[114:115], v[116:117], s[16:17], v[0:1] op_sel_hi:[1,0,1]
	v_exp_f32_e32 v8, v8
	v_exp_f32_e32 v9, v9
	v_exp_f32_e32 v134, v114
	v_exp_f32_e32 v135, v115
	v_pk_fma_f32 v[114:115], v[118:119], s[16:17], v[0:1] op_sel_hi:[1,0,1]
	v_pk_add_f32 v[112:113], v[8:9], v[112:113]
	v_exp_f32_e32 v138, v114
	v_exp_f32_e32 v139, v115
	v_pk_fma_f32 v[114:115], v[120:121], s[16:17], v[0:1] op_sel_hi:[1,0,1]
	v_pk_add_f32 v[112:113], v[134:135], v[112:113]
	v_exp_f32_e32 v142, v114
	v_exp_f32_e32 v143, v115
	v_pk_fma_f32 v[114:115], v[122:123], s[16:17], v[0:1] op_sel_hi:[1,0,1]
	v_pk_add_f32 v[112:113], v[138:139], v[112:113]
	v_exp_f32_e32 v144, v114
	v_exp_f32_e32 v145, v115
	v_pk_fma_f32 v[114:115], v[124:125], s[16:17], v[0:1] op_sel_hi:[1,0,1]
	v_pk_fma_f32 v[0:1], v[126:127], s[16:17], v[0:1] op_sel_hi:[1,0,1]
	v_exp_f32_e32 v146, v114
	v_exp_f32_e32 v147, v115
	v_exp_f32_e32 v148, v0
	v_exp_f32_e32 v149, v1
	v_pk_add_f32 v[112:113], v[142:143], v[112:113]
	v_cvt_pk_bf16_f32 v4, v4, v5
	v_pk_add_f32 v[112:113], v[144:145], v[112:113]
	v_cvt_pk_bf16_f32 v5, v8, v9
	v_pk_add_f32 v[112:113], v[146:147], v[112:113]
	s_add_u32 s0, s0, 0x6000000
	v_pk_add_f32 v[0:1], v[148:149], v[112:113]
	s_addc_u32 s1, s1, 0
	v_add_f32_e32 v0, v0, v1
	v_add_f32_e32 v155, v207, v0
	v_pk_fma_f32 v[0:1], v[96:97], s[16:17], v[190:191] op_sel_hi:[1,0,1]
	v_pk_fma_f32 v[96:97], v[98:99], s[16:17], v[190:191] op_sel_hi:[1,0,1]
	v_exp_f32_e32 v126, v0
	v_exp_f32_e32 v127, v1
	v_exp_f32_e32 v128, v96
	v_exp_f32_e32 v129, v97
	v_pk_fma_f32 v[96:97], v[100:101], s[16:17], v[190:191] op_sel_hi:[1,0,1]
	v_pk_add_f32 v[0:1], v[126:127], 0 op_sel_hi:[1,0]
	v_exp_f32_e32 v130, v96
	v_exp_f32_e32 v131, v97
	v_pk_fma_f32 v[96:97], v[102:103], s[16:17], v[190:191] op_sel_hi:[1,0,1]
	v_pk_add_f32 v[0:1], v[128:129], v[0:1]
	v_exp_f32_e32 v132, v96
	v_exp_f32_e32 v133, v97
	v_pk_fma_f32 v[96:97], v[104:105], s[16:17], v[190:191] op_sel_hi:[1,0,1]
	v_pk_add_f32 v[0:1], v[130:131], v[0:1]
	v_exp_f32_e32 v118, v96
	v_exp_f32_e32 v119, v97
	v_pk_fma_f32 v[96:97], v[106:107], s[16:17], v[190:191] op_sel_hi:[1,0,1]
	v_pk_add_f32 v[0:1], v[132:133], v[0:1]
	v_exp_f32_e32 v120, v96
	v_exp_f32_e32 v121, v97
	v_pk_fma_f32 v[96:97], v[108:109], s[16:17], v[190:191] op_sel_hi:[1,0,1]
	v_pk_add_f32 v[0:1], v[118:119], v[0:1]
	v_exp_f32_e32 v122, v96
	v_exp_f32_e32 v123, v97
	v_pk_fma_f32 v[96:97], v[110:111], s[16:17], v[190:191] op_sel_hi:[1,0,1]
	v_exp_f32_e32 v110, v80
	v_exp_f32_e32 v124, v96
	v_exp_f32_e32 v125, v97
	v_exp_f32_e32 v111, v81
	v_pk_fma_f32 v[80:81], v[82:83], s[16:17], v[190:191] op_sel_hi:[1,0,1]
	v_pk_add_f32 v[0:1], v[120:121], v[0:1]
	v_exp_f32_e32 v112, v80
	v_exp_f32_e32 v113, v81
	v_pk_fma_f32 v[80:81], v[84:85], s[16:17], v[190:191] op_sel_hi:[1,0,1]
	v_pk_add_f32 v[0:1], v[122:123], v[0:1]
	v_exp_f32_e32 v114, v80
	v_exp_f32_e32 v115, v81
	v_pk_fma_f32 v[80:81], v[86:87], s[16:17], v[190:191] op_sel_hi:[1,0,1]
	v_pk_add_f32 v[0:1], v[124:125], v[0:1]
	v_exp_f32_e32 v116, v80
	v_exp_f32_e32 v117, v81
	v_pk_add_f32 v[0:1], v[110:111], v[0:1]
	v_pk_fma_f32 v[82:83], v[90:91], s[16:17], v[190:191] op_sel_hi:[1,0,1]
	v_pk_add_f32 v[0:1], v[112:113], v[0:1]
	v_exp_f32_e32 v104, v82
	v_pk_add_f32 v[0:1], v[114:115], v[0:1]
	v_exp_f32_e32 v105, v83
	v_pk_add_f32 v[80:81], v[116:117], v[0:1]
	v_pk_fma_f32 v[0:1], v[88:89], s[16:17], v[190:191] op_sel_hi:[1,0,1]
	v_pk_fma_f32 v[82:83], v[92:93], s[16:17], v[190:191] op_sel_hi:[1,0,1]
	v_exp_f32_e32 v0, v0
	v_exp_f32_e32 v1, v1
	v_exp_f32_e32 v106, v82
	v_exp_f32_e32 v107, v83
	v_pk_fma_f32 v[82:83], v[94:95], s[16:17], v[190:191] op_sel_hi:[1,0,1]
	v_pk_add_f32 v[80:81], v[0:1], v[80:81]
	v_exp_f32_e32 v108, v82
	v_exp_f32_e32 v109, v83
	v_pk_add_f32 v[80:81], v[104:105], v[80:81]
	v_add_u32_e32 v98, v204, v205
	v_pk_add_f32 v[80:81], v[106:107], v[80:81]
	ds_read_b64_tr_b16 v[84:85], v98 offset:27648
	ds_read_b64_tr_b16 v[86:87], v98 offset:28800
	v_pk_add_f32 v[80:81], v[108:109], v[80:81]
	v_cvt_pk_bf16_f32 v82, v150, v151
	v_add_f32_e32 v80, v80, v81
	v_add_f32_e32 v154, v206, v80
	v_cvt_pk_bf16_f32 v80, v12, v13
	v_cvt_pk_bf16_f32 v81, v14, v15
	ds_read_b64_tr_b16 v[12:13], v98 offset:27712
	ds_read_b64_tr_b16 v[14:15], v98 offset:28864
	v_cvt_pk_bf16_f32 v83, v152, v153
	ds_read_b64_tr_b16 v[92:93], v98 offset:29952
	ds_read_b64_tr_b16 v[94:95], v98 offset:31104
	s_waitcnt lgkmcnt(4)
; #define MFMA32(a, b, c) __builtin_amdgcn_mfma_f32_32x32x16_bf16((a), (b), (c), 0, 0, 0)
; template <int DK, int DV, int MODE, int QB, bool PACK = false>
; DI void attn_item(const AttArgs& a, int q0, int t_lo, int t_hi) {
;     ...
; #pragma unroll
;       for (int qb = 0; qb < QB; ++qb)
; #pragma unroll
;         for (int kb = 0; kb < 2; ++kb)
; #pragma unroll
;           for (int st = 0; st < 2; ++st) {
;             u32x4 pk;
;             pk[0] = pack2(s[qb][kb][8 * st + 0], s[qb][kb][8 * st + 1]);
;             pk[1] = pack2(s[qb][kb][8 * st + 2], s[qb][kb][8 * st + 3]);
;             pk[2] = pack2(s[qb][kb][8 * st + 4], s[qb][kb][8 * st + 5]);
;             pk[3] = pack2(s[qb][kb][8 * st + 6], s[qb][kb][8 * st + 7]);
;             const bf16x8 pf = __builtin_bit_cast(bf16x8, pk);
;             const unsigned char* vrow = Vb + (kb * 32 + 16 * st + 4 * h + vq) * VST + (16 * vblk + 4 * vp) * 2;
; #pragma unroll
;             for (int d = 0; d < NDB; ++d) {
;               s16x4 lo = __builtin_amdgcn_ds_read_tr16_b64_v4i16((s16x4 __attribute__((address_space(3)))*)(vrow + d * 64));
;               s16x4 hi = __builtin_amdgcn_ds_read_tr16_b64_v4i16((s16x4 __attribute__((address_space(3)))*)(vrow + 8 * VST + d * 64));
;               const bf16x8 vf = __builtin_shufflevector(lo, hi, 0, 1, 2, 3, 4, 5, 6, 7);
;               o[qb][d] = MFMA32(vf, pf, o[qb][d]);
;             }
;           }
;     }
;     __syncthreads();
	v_mfma_f32_32x32x16_bf16 v[64:79], v[84:87], v[80:83], v[64:79]
	ds_read_b64_tr_b16 v[88:89], v98 offset:30016
	ds_read_b64_tr_b16 v[90:91], v98 offset:31168
	v_cvt_pk_bf16_f32 v100, v142, v143
	v_cvt_pk_bf16_f32 v101, v144, v145
	v_cvt_pk_bf16_f32 v102, v146, v147
	v_cvt_pk_bf16_f32 v103, v148, v149
	s_waitcnt lgkmcnt(4)
	v_mfma_f32_32x32x16_bf16 v[48:63], v[12:15], v[80:83], v[48:63]
	v_cvt_pk_bf16_f32 v80, v6, v7
	v_cvt_pk_bf16_f32 v81, v10, v11
	v_cvt_pk_bf16_f32 v82, v136, v137
	v_cvt_pk_bf16_f32 v83, v140, v141
	v_cvt_pk_bf16_f32 v6, v134, v135
	v_cvt_pk_bf16_f32 v7, v138, v139
	s_waitcnt lgkmcnt(2)
	v_mfma_f32_32x32x16_bf16 v[64:79], v[92:95], v[80:83], v[64:79]
	s_waitcnt lgkmcnt(0)
	v_mfma_f32_32x32x16_bf16 v[48:63], v[88:91], v[80:83], v[48:63]
	ds_read_b64_tr_b16 v[80:81], v98 offset:32256
	ds_read_b64_tr_b16 v[82:83], v98 offset:33408
	ds_read_b64_tr_b16 v[8:9], v98 offset:32320
	ds_read_b64_tr_b16 v[10:11], v98 offset:33472
	s_waitcnt lgkmcnt(2)
	v_mfma_f32_32x32x16_bf16 v[64:79], v[80:83], v[4:7], v[64:79]
	s_waitcnt lgkmcnt(0)
	v_mfma_f32_32x32x16_bf16 v[48:63], v[8:11], v[4:7], v[48:63]
	ds_read_b64_tr_b16 v[4:5], v98 offset:34560
	ds_read_b64_tr_b16 v[6:7], v98 offset:35712
	ds_read_b64_tr_b16 v[96:97], v98 offset:34624
	ds_read_b64_tr_b16 v[98:99], v98 offset:35776
	s_waitcnt lgkmcnt(0)
	s_barrier
; #define MFMA32(a, b, c) __builtin_amdgcn_mfma_f32_32x32x16_bf16((a), (b), (c), 0, 0, 0)
; DI float fexp2(float x) { return __builtin_amdgcn_exp2f(x); }
; template <int DK, int DV, int MODE, int QB, bool PACK = false>
; DI void attn_item(const AttArgs& a, int q0, int t_lo, int t_hi) {
;     ...
;               s16x4 lo = __builtin_amdgcn_ds_read_tr16_b64_v4i16((s16x4 __attribute__((address_space(3)))*)(vrow + d * 64));
;               s16x4 hi = __builtin_amdgcn_ds_read_tr16_b64_v4i16((s16x4 __attribute__((address_space(3)))*)(vrow + 8 * VST + d * 64));
;               const bf16x8 vf = __builtin_shufflevector(lo, hi, 0, 1, 2, 3, 4, 5, 6, 7);
;               o[qb][d] = MFMA32(vf, pf, o[qb][d]);
;             }
;           }
;     }
;     __syncthreads();
;   }
; #pragma unroll
;   for (int qb = 0; qb < QB; ++qb) {
;     float lt = lsum[qb] + __shfl_xor(lsum[qb], 32);
;     if constexpr (MODE == 1) lt += fexp2(((PACK ? a.sinkp[hg] : a.sink) - m[qb] * scale) * LOG2E);
;     const float inv = 1.f / lt;
;     bf16_t* op = a.o + hg * DV + (size_t)(wq0 + qb * 32 + r) * a.ldo + 8 * h;
; #pragma unroll
;     for (int d = 0; d < NDB; ++d)
; #pragma unroll
;       for (int pr = 0; pr < 2; ++pr) {
;         const int ia = 8 * pr, ib = 8 * pr + 4;
;         const unsigned ax = pack2(o[qb][d][ia] * inv, o[qb][d][ia + 1] * inv), ay = pack2(o[qb][d][ia + 2] * inv, o[qb][d][ia + 3] * inv);
;         const unsigned bx = pack2(o[qb][d][ib] * inv, o[qb][d][ib + 1] * inv), by = pack2(o[qb][d][ib + 2] * inv, o[qb][d][ib + 3] * inv);
;         const u32x2 sx = __builtin_amdgcn_permlane32_swap(ax, bx, false, false);
;         const u32x2 sy = __builtin_amdgcn_permlane32_swap(ay, by, false, false);
;         uint4 st;
;         st.x = sx[0]; st.y = sy[0]; st.z = sx[1]; st.w = sy[1];
;         *(uint4*)(op + 32 * d + 16 * pr) = st;
;       }
	v_mfma_f32_32x32x16_bf16 v[64:79], v[4:7], v[100:103], v[64:79]
	v_mfma_f32_32x32x16_bf16 v[48:63], v[96:99], v[100:103], v[48:63]
	v_cvt_pk_bf16_f32 v100, v126, v127
	v_cvt_pk_bf16_f32 v101, v128, v129
	v_cvt_pk_bf16_f32 v102, v130, v131
	v_cvt_pk_bf16_f32 v103, v132, v133
	s_nop 1
	v_mfma_f32_32x32x16_bf16 v[32:47], v[84:87], v[100:103], v[32:47]
	v_mfma_f32_32x32x16_bf16 v[16:31], v[12:15], v[100:103], v[16:31]
	v_cvt_pk_bf16_f32 v12, v118, v119
	v_cvt_pk_bf16_f32 v13, v120, v121
	v_cvt_pk_bf16_f32 v14, v122, v123
	v_cvt_pk_bf16_f32 v15, v124, v125
	s_nop 1
	v_mfma_f32_32x32x16_bf16 v[32:47], v[92:95], v[12:15], v[32:47]
	v_mfma_f32_32x32x16_bf16 v[16:31], v[88:91], v[12:15], v[16:31]
	v_cvt_pk_bf16_f32 v12, v110, v111
	v_cvt_pk_bf16_f32 v13, v112, v113
	v_cvt_pk_bf16_f32 v14, v114, v115
	v_cvt_pk_bf16_f32 v15, v116, v117
	s_nop 1
	v_mfma_f32_32x32x16_bf16 v[32:47], v[80:83], v[12:15], v[32:47]
	v_mfma_f32_32x32x16_bf16 v[16:31], v[8:11], v[12:15], v[16:31]
	v_cvt_pk_bf16_f32 v8, v0, v1
	ds_bpermute_b32 v0, v213, v155
	v_cvt_pk_bf16_f32 v9, v104, v105
	v_cvt_pk_bf16_f32 v10, v106, v107
	v_cvt_pk_bf16_f32 v11, v108, v109
	s_waitcnt lgkmcnt(0)
	v_add_f32_e32 v0, v155, v0
	v_div_scale_f32 v1, s[2:3], v0, v0, 1.0
	v_mfma_f32_32x32x16_bf16 v[32:47], v[4:7], v[8:11], v[32:47]
	v_rcp_f32_e32 v4, v1
	s_nop 0
	v_fma_f32 v5, -v1, v4, 1.0
	v_fmac_f32_e32 v4, v5, v4
	v_div_scale_f32 v5, vcc, 1.0, v0, 1.0
	v_mul_f32_e32 v6, v5, v4
	v_fma_f32 v7, -v1, v6, v5
	v_fmac_f32_e32 v6, v7, v4
	v_fma_f32 v1, -v1, v6, v5
	v_div_fmas_f32 v1, v1, v4, v6
	v_lshlrev_b64 v[4:5], 11, v[186:187]
	v_mfma_f32_32x32x16_bf16 v[16:31], v[96:99], v[8:11], v[16:31]
	v_div_fixup_f32 v0, v1, v0, 1.0
	v_lshl_add_u64 v[4:5], s[0:1], 0, v[4:5]
	v_lshlrev_b32_e32 v8, 1, v189
	v_mov_b32_e32 v9, v2
	v_lshl_add_u64 v[10:11], v[4:5], 0, v[8:9]
	v_pk_mul_f32 v[4:5], v[64:65], v[0:1] op_sel_hi:[1,0]
	v_pk_mul_f32 v[6:7], v[66:67], v[0:1] op_sel_hi:[1,0]
	v_cvt_pk_bf16_f32 v4, v4, v5
	v_cvt_pk_bf16_f32 v5, v6, v7
	v_pk_mul_f32 v[6:7], v[68:69], v[0:1] op_sel_hi:[1,0]
	v_pk_mul_f32 v[12:13], v[70:71], v[0:1] op_sel_hi:[1,0]
	v_cvt_pk_bf16_f32 v6, v6, v7
	v_cvt_pk_bf16_f32 v7, v12, v13
	s_nop 0
	v_permlane32_swap_b32_e32 v4, v6
	v_permlane32_swap_b32_e32 v5, v7
	global_store_dwordx4 v[10:11], v[4:7], off
	v_pk_mul_f32 v[12:13], v[78:79], v[0:1] op_sel_hi:[1,0]
	s_nop 0
	v_pk_mul_f32 v[4:5], v[72:73], v[0:1] op_sel_hi:[1,0]
	v_pk_mul_f32 v[6:7], v[74:75], v[0:1] op_sel_hi:[1,0]
	v_cvt_pk_bf16_f32 v4, v4, v5
	v_cvt_pk_bf16_f32 v5, v6, v7
	v_pk_mul_f32 v[6:7], v[76:77], v[0:1] op_sel_hi:[1,0]
	s_nop 0
	v_cvt_pk_bf16_f32 v6, v6, v7
	v_cvt_pk_bf16_f32 v7, v12, v13
	s_nop 0
	v_permlane32_swap_b32_e32 v4, v6
	v_permlane32_swap_b32_e32 v5, v7
	global_store_dwordx4 v[10:11], v[4:7], off offset:32
	v_pk_mul_f32 v[12:13], v[54:55], v[0:1] op_sel_hi:[1,0]
	s_nop 0
	v_pk_mul_f32 v[4:5], v[48:49], v[0:1] op_sel_hi:[1,0]
	v_pk_mul_f32 v[6:7], v[50:51], v[0:1] op_sel_hi:[1,0]
	v_cvt_pk_bf16_f32 v4, v4, v5
	v_cvt_pk_bf16_f32 v5, v6, v7
	v_pk_mul_f32 v[6:7], v[52:53], v[0:1] op_sel_hi:[1,0]
	s_nop 0
	v_cvt_pk_bf16_f32 v6, v6, v7
	v_cvt_pk_bf16_f32 v7, v12, v13
	s_nop 0
	v_permlane32_swap_b32_e32 v4, v6
	v_permlane32_swap_b32_e32 v5, v7
	global_store_dwordx4 v[10:11], v[4:7], off offset:64
	s_nop 1
	v_pk_mul_f32 v[4:5], v[56:57], v[0:1] op_sel_hi:[1,0]
	v_pk_mul_f32 v[6:7], v[58:59], v[0:1] op_sel_hi:[1,0]
	v_cvt_pk_bf16_f32 v4, v4, v5
	v_cvt_pk_bf16_f32 v5, v6, v7
	v_pk_mul_f32 v[6:7], v[60:61], v[0:1] op_sel_hi:[1,0]
	v_pk_mul_f32 v[0:1], v[62:63], v[0:1] op_sel_hi:[1,0]
	v_cvt_pk_bf16_f32 v6, v6, v7
	v_cvt_pk_bf16_f32 v7, v0, v1
	ds_bpermute_b32 v0, v213, v154
	v_permlane32_swap_b32_e32 v4, v6
	v_permlane32_swap_b32_e32 v5, v7
	s_waitcnt lgkmcnt(0)
	v_add_f32_e32 v0, v154, v0
	v_div_scale_f32 v1, s[2:3], v0, v0, 1.0
	v_rcp_f32_e32 v3, v1
	global_store_dwordx4 v[10:11], v[4:7], off offset:96
	s_nop 1
	v_fma_f32 v4, -v1, v3, 1.0
	v_fmac_f32_e32 v3, v4, v3
	v_div_scale_f32 v4, vcc, 1.0, v0, 1.0
	v_mul_f32_e32 v5, v4, v3
	v_fma_f32 v6, -v1, v5, v4
	v_fmac_f32_e32 v5, v6, v3
	v_fma_f32 v1, -v1, v5, v4
	v_div_fmas_f32 v1, v1, v3, v5
	v_div_fixup_f32 v10, v1, v0, 1.0
	v_lshlrev_b64 v[0:1], 11, v[184:185]
	v_lshl_add_u64 v[0:1], s[0:1], 0, v[0:1]
	v_pk_mul_f32 v[4:5], v[32:33], v[10:11] op_sel_hi:[1,0]
	v_pk_mul_f32 v[6:7], v[34:35], v[10:11] op_sel_hi:[1,0]
	v_lshl_add_u64 v[0:1], v[0:1], 0, v[8:9]
	v_cvt_pk_bf16_f32 v4, v4, v5
	v_cvt_pk_bf16_f32 v5, v6, v7
	v_pk_mul_f32 v[6:7], v[36:37], v[10:11] op_sel_hi:[1,0]
	v_pk_mul_f32 v[8:9], v[38:39], v[10:11] op_sel_hi:[1,0]
	v_cvt_pk_bf16_f32 v6, v6, v7
	v_cvt_pk_bf16_f32 v7, v8, v9
	s_nop 0
	v_permlane32_swap_b32_e32 v4, v6
	v_permlane32_swap_b32_e32 v5, v7
	global_store_dwordx4 v[0:1], v[4:7], off
	v_pk_mul_f32 v[8:9], v[46:47], v[10:11] op_sel_hi:[1,0]
	s_nop 0
	v_pk_mul_f32 v[4:5], v[40:41], v[10:11] op_sel_hi:[1,0]
	v_pk_mul_f32 v[6:7], v[42:43], v[10:11] op_sel_hi:[1,0]
	v_cvt_pk_bf16_f32 v4, v4, v5
	v_cvt_pk_bf16_f32 v5, v6, v7
	v_pk_mul_f32 v[6:7], v[44:45], v[10:11] op_sel_hi:[1,0]
	s_nop 0
	v_cvt_pk_bf16_f32 v6, v6, v7
	v_cvt_pk_bf16_f32 v7, v8, v9
	s_nop 0
	v_permlane32_swap_b32_e32 v4, v6
	v_permlane32_swap_b32_e32 v5, v7
	global_store_dwordx4 v[0:1], v[4:7], off offset:32
	v_pk_mul_f32 v[8:9], v[22:23], v[10:11] op_sel_hi:[1,0]
	s_nop 0
	v_pk_mul_f32 v[4:5], v[16:17], v[10:11] op_sel_hi:[1,0]
	v_pk_mul_f32 v[6:7], v[18:19], v[10:11] op_sel_hi:[1,0]
	v_cvt_pk_bf16_f32 v4, v4, v5
	v_cvt_pk_bf16_f32 v5, v6, v7
	v_pk_mul_f32 v[6:7], v[20:21], v[10:11] op_sel_hi:[1,0]
	s_nop 0
	v_cvt_pk_bf16_f32 v6, v6, v7
	v_cvt_pk_bf16_f32 v7, v8, v9
	s_nop 0
	v_permlane32_swap_b32_e32 v4, v6
	v_permlane32_swap_b32_e32 v5, v7
	global_store_dwordx4 v[0:1], v[4:7], off offset:64
	v_pk_mul_f32 v[8:9], v[30:31], v[10:11] op_sel_hi:[1,0]
	s_nop 0
	v_pk_mul_f32 v[4:5], v[24:25], v[10:11] op_sel_hi:[1,0]
	v_pk_mul_f32 v[6:7], v[26:27], v[10:11] op_sel_hi:[1,0]
	v_cvt_pk_bf16_f32 v4, v4, v5
	v_cvt_pk_bf16_f32 v5, v6, v7
	v_pk_mul_f32 v[6:7], v[28:29], v[10:11] op_sel_hi:[1,0]
	s_nop 0
	v_cvt_pk_bf16_f32 v6, v6, v7
	v_cvt_pk_bf16_f32 v7, v8, v9
	s_nop 0
	v_permlane32_swap_b32_e32 v4, v6
	v_permlane32_swap_b32_e32 v5, v7

; template <int DK, int DV, int MODE, int QB, bool PACK = false>
; DI void attn_item(const AttArgs& a, int q0, int t_lo, int t_hi) {
;     ...
;   f32x16 o[QB][NDB];
;   float m[QB], lsum[QB];
; #pragma unroll
;   for (int qb = 0; qb < QB; ++qb) {
;     m[qb] = -1e30f; lsum[qb] = 0.f;
; #pragma unroll
;     for (int d = 0; d < NDB; ++d)
; #pragma unroll
;       for (int i = 0; i < 16; ++i) o[qb][d][i] = 0.f;
;   }
;   u32x4 kr[NKL], vr[NVL];
;   att_gload<DK, DV, MODE>(a, t_lo, kr, vr);
;   att_swrite<DK, DV>(0, kr, vr);
;   if (t_lo + 1 < t_hi) att_gload<DK, DV, MODE>(a, t_lo + 1, kr, vr);
;   __syncthreads();
;   const float scale = a.scale;
;   const float cexp = (MODE == 2) ? LOG2E : a.scale * LOG2E;
;   const int vq = (l & 15) >> 2, vp = l & 3, vblk = (l >> 4) & 1;
.LBB0_834:
	s_or_b64 exec, exec, s[4:5]
	s_waitcnt vmcnt(1)
	v_add_u32_e32 v8, v12, v14
	s_waitcnt vmcnt(0)
	ds_write_b128 v8, v[4:7] offset:9216
	v_mov_b32_e32 v8, v224
	s_mov_b32 s4, 0x40000
	v_min_i32_e32 v5, 0x1ff, v8
	v_ashrrev_i32_e32 v4, 31, v5
	v_lshrrev_b32_e32 v4, 29, v4
	v_add_u32_e32 v6, v5, v4
	v_ashrrev_i32_e32 v4, 3, v6
	v_and_b32_e32 v6, 0x1ffffff8, v6
	v_sub_u32_e32 v6, v5, v6
	v_ashrrev_i32_e32 v5, 31, v4
	v_lshlrev_b64 v[4:5], 12, v[4:5]
	v_lshlrev_b32_e32 v6, 3, v6
	v_ashrrev_i32_e32 v7, 31, v6
	v_lshl_add_u64 v[4:5], s[2:3], 0, v[4:5]
	v_lshl_add_u64 v[4:5], v[6:7], 1, v[4:5]
	v_ashrrev_i32_e32 v6, 31, v8
	v_lshrrev_b32_e32 v6, 29, v6
	v_add_u32_e32 v7, v8, v6
	v_ashrrev_i32_e32 v6, 3, v7
	v_and_b32_e32 v7, 0x1ffffff8, v7
	v_sub_u32_e32 v8, v8, v7
	v_ashrrev_i32_e32 v7, 31, v6
	v_lshlrev_b64 v[6:7], 12, v[6:7]
	v_lshlrev_b32_e32 v8, 3, v8
	v_add_co_u32_e32 v4, vcc, s4, v4
	v_ashrrev_i32_e32 v9, 31, v8
	v_lshl_add_u64 v[6:7], s[2:3], 0, v[6:7]
	v_addc_co_u32_e32 v5, vcc, 0, v5, vcc
	v_lshl_add_u64 v[6:7], v[8:9], 1, v[6:7]
	v_add_co_u32_e32 v6, vcc, s4, v6
	v_lshlrev_b32_e32 v189, 3, v3
	s_nop 0
	v_addc_co_u32_e32 v7, vcc, 0, v7, vcc
	global_load_dwordx4 v[176:179], v[4:5], off offset:1024
	global_load_dwordx4 v[180:183], v[6:7], off offset:1280
	v_bfe_u32 v4, v1, 2, 2
	v_and_b32_e32 v5, 16, v1
	v_lshlrev_b32_e32 v1, 2, v1
	v_lshl_or_b32 v3, v3, 2, v4
	v_and_or_b32 v1, v1, 12, v5
	v_mov_b32_e32 v14, v2
	v_mov_b32_e32 v15, v2
	v_lshlrev_b32_e32 v204, 1, v1
	v_mul_u32_u24_e32 v208, 0x90, v0
	v_mul_u32_u24_e32 v205, 0x90, v3
	v_mov_b32_e32 v0, v2
	v_mov_b32_e32 v1, v2
	v_mov_b32_e32 v3, v2
	v_mov_b32_e32 v4, v2
	v_mov_b32_e32 v5, v2
	v_mov_b32_e32 v6, v2
	v_mov_b32_e32 v7, v2
	v_mov_b32_e32 v8, v2
	v_mov_b32_e32 v9, v2
	v_mov_b32_e32 v10, v2
	v_mov_b32_e32 v11, v2
	v_mov_b32_e32 v12, v2
	v_mov_b32_e32 v13, v2
	v_mov_b64_e32 v[30:31], v[14:15]
	v_mov_b64_e32 v[46:47], v[14:15]
	v_mov_b64_e32 v[62:63], v[14:15]
	v_mov_b64_e32 v[78:79], v[14:15]
	s_lshl_b32 s8, s6, 6
	s_mov_b32 s9, 0
	v_mov_b32_e32 v206, 0
	v_mov_b32_e32 v191, 0xf149f2ca
	s_add_u32 s4, s2, 0x80000
	s_addc_u32 s5, s3, 0
	v_lshrrev_b32_e32 v210, 3, v224
	v_and_b32_e32 v211, 7, v224
	v_lshlrev_b32_e32 v212, 12, v210
	v_lshl_or_b32 v212, v211, 4, v212
	v_mul_u32_u24_e32 v210, 0x90, v210
	v_lshl_add_u32 v210, v211, 4, v210
	v_mov_b64_e32 v[28:29], v[12:13]
	v_mov_b64_e32 v[26:27], v[10:11]
	v_mov_b64_e32 v[24:25], v[8:9]
	v_mov_b64_e32 v[22:23], v[6:7]
	v_mov_b64_e32 v[20:21], v[4:5]
	v_mov_b64_e32 v[18:19], v[2:3]
	v_mov_b64_e32 v[16:17], v[0:1]
	v_mov_b64_e32 v[44:45], v[12:13]
	v_mov_b64_e32 v[42:43], v[10:11]
	v_mov_b64_e32 v[40:41], v[8:9]
	v_mov_b64_e32 v[38:39], v[6:7]
	v_mov_b64_e32 v[36:37], v[4:5]
	v_mov_b64_e32 v[34:35], v[2:3]
	v_mov_b64_e32 v[32:33], v[0:1]
	v_mov_b64_e32 v[60:61], v[12:13]
	v_mov_b64_e32 v[58:59], v[10:11]
	v_mov_b64_e32 v[56:57], v[8:9]
	v_mov_b64_e32 v[54:55], v[6:7]
	v_mov_b64_e32 v[52:53], v[4:5]
	v_mov_b64_e32 v[50:51], v[2:3]
	v_mov_b64_e32 v[48:49], v[0:1]
	v_mov_b64_e32 v[76:77], v[12:13]
	v_mov_b64_e32 v[74:75], v[10:11]
	v_mov_b64_e32 v[72:73], v[8:9]
	v_mov_b64_e32 v[70:71], v[6:7]
	v_mov_b64_e32 v[68:69], v[4:5]
	v_mov_b64_e32 v[66:67], v[2:3]
	v_mov_b64_e32 v[64:65], v[0:1]
	v_mov_b32_e32 v1, 0xf149f2ca
	v_mov_b32_e32 v207, 0
	v_and_b32_e32 v213, 64, v225
	v_xor_b32_e32 v214, 32, v225
	v_add_u32_e32 v213, 64, v213
	v_cmp_lt_i32_e32 vcc, v214, v213
	v_cndmask_b32_e32 v214, v225, v214, vcc
	v_lshlrev_b32_e32 v213, 2, v214
	v_add_u32_e32 v214, v188, v208
	s_waitcnt lgkmcnt(0)
	s_barrier
	s_branch .LBB0_836

; #define MFMA32(a, b, c) __builtin_amdgcn_mfma_f32_32x32x16_bf16((a), (b), (c), 0, 0, 0)
; DI int crow(int i, int h) { return (i & 3) + 8 * (i >> 2) + 4 * h; }
; DI float fexp2(float x) { return __builtin_amdgcn_exp2f(x); }
; template <int DK, int DV, int MODE, int QB, bool PACK = false>
; DI void attn_item(const AttArgs& a, int q0, int t_lo, int t_hi) {
;     ...
;       f32x16 s[QB][2];
; #pragma unroll
;       for (int qb = 0; qb < QB; ++qb)
; #pragma unroll
;         for (int kb = 0; kb < 2; ++kb) {
; #pragma unroll
;           for (int i = 0; i < 16; ++i) s[qb][kb][i] = 0.f;
;           const unsigned char* kp = Kb + (kb * 32 + r) * KST + h * 16;
; #pragma unroll
;           for (int st = 0; st < NKS; ++st) {
;             const bf16x8 kf = *(const bf16x8*)(kp + st * 32);
;             s[qb][kb] = MFMA32(kf, qf[qb][st], s[qb][kb]);
;           }
;         }
; #pragma unroll
;       for (int qb = 0; qb < QB; ++qb) {
;         const int qidx = wq0 + qb * 32 + r;
;         float mloc = -1e30f;
; #pragma unroll
;         for (int kb = 0; kb < 2; ++kb)
; #pragma unroll
;           for (int i = 0; i < 16; ++i) {
;             float tt = s[qb][kb][i];
;             if constexpr (MODE == 1) {
;               const int kidx = tile * 64 + kb * 32 + crow(i, h);
;               const int d = kidx - qidx;
;               tt = (d <= 128 && d >= -128) ? tt : -1e30f;
;               s[qb][kb][i] = tt;
;             }
;             if constexpr (MODE == 2) {
;               const int kc = kb * 32 + crow(i, h);
;               const bool ok = (kc >= c0[qb]) && (kc < c0[qb] + 16);
;               const int bi = ok ? ((tile - rq + 7) * 31 + kc - cq[qb] + 15) : 0;
;               tt = ok ? fmaf(tt, scale, rpbs[bi]) : -1e30f;
;               s[qb][kb][i] = tt;
;             }
;             mloc = fmaxf(mloc, tt);
;           }
;         mloc = fmaxf(mloc, __shfl_xor(mloc, 32));
;         if (__any((mloc - m[qb]) * cexp > 8.f)) {
;           const float mnew = fmaxf(m[qb], mloc);
;           const float alpha = fexp2((m[qb] - mnew) * cexp);
;           m[qb] = mnew;
;           lsum[qb] *= alpha;
; #pragma unroll
;           for (int d = 0; d < NDB; ++d)
; #pragma unroll
;             for (int i = 0; i < 16; ++i) o[qb][d][i] *= alpha;
;         }
.LBB0_842:
	s_mul_i32 s6, s13, 0x4800
	v_add_u32_e32 v0, s6, v214
	ds_read_b128 v[4:7], v0
	ds_read_b128 v[8:11], v0 offset:32
	ds_read_b128 v[84:87], v0 offset:4608
	ds_read_b128 v[12:15], v0 offset:64
	ds_read_b128 v[192:195], v0 offset:4640
	s_waitcnt lgkmcnt(4)
	v_mfma_f32_32x32x16_bf16 v[128:143], v[4:7], v[172:175], 0
	ds_read_b128 v[80:83], v0 offset:96
	ds_read_b128 v[196:199], v0 offset:4672
	ds_read_b128 v[200:203], v0 offset:4704
	v_mfma_f32_32x32x16_bf16 v[96:111], v[4:7], v[144:147], 0
	s_mov_b32 s7, 0xf149f2ca
	s_waitcnt lgkmcnt(6)
	v_mfma_f32_32x32x16_bf16 v[128:143], v[8:11], v[168:171], v[128:143]
	s_waitcnt lgkmcnt(5)
	v_mfma_f32_32x32x16_bf16 v[112:127], v[84:87], v[172:175], 0
	v_mfma_f32_32x32x16_bf16 v[96:111], v[8:11], v[148:151], v[96:111]
	s_waitcnt lgkmcnt(4)
	v_mfma_f32_32x32x16_bf16 v[128:143], v[12:15], v[164:167], v[128:143]
	s_waitcnt lgkmcnt(3)
	v_mfma_f32_32x32x16_bf16 v[112:127], v[192:195], v[168:171], v[112:127]
	v_mfma_f32_32x32x16_bf16 v[96:111], v[12:15], v[152:155], v[96:111]
	s_waitcnt lgkmcnt(2)
	v_mfma_f32_32x32x16_bf16 v[128:143], v[80:83], v[160:163], v[128:143]
	s_waitcnt lgkmcnt(1)
	v_mfma_f32_32x32x16_bf16 v[112:127], v[196:199], v[164:167], v[112:127]
	s_nop 9
	v_max3_f32 v0, v128, s7, v129
	v_max3_f32 v0, v0, v130, v131
	v_max3_f32 v0, v0, v132, v133
	v_max3_f32 v0, v0, v134, v135
	v_max3_f32 v0, v0, v136, v137
	v_max3_f32 v0, v0, v138, v139
	v_max3_f32 v0, v0, v140, v141
	v_mfma_f32_32x32x16_bf16 v[96:111], v[80:83], v[156:159], v[96:111]
	v_max3_f32 v0, v0, v142, v143
	s_mov_b32 s7, 0x41000000
	v_mfma_f32_32x32x16_bf16 v[80:95], v[84:87], v[144:147], 0
	s_waitcnt lgkmcnt(0)
	v_mfma_f32_32x32x16_bf16 v[112:127], v[200:203], v[160:163], v[112:127]
	v_mfma_f32_32x32x16_bf16 v[80:95], v[192:195], v[148:151], v[80:95]
	s_nop 10
	v_max3_f32 v0, v0, v112, v113
	v_max3_f32 v0, v0, v114, v115
	v_max3_f32 v0, v0, v116, v117
	v_max3_f32 v0, v0, v118, v119
	v_max3_f32 v0, v0, v120, v121
	v_max3_f32 v0, v0, v122, v123
	v_max3_f32 v0, v0, v124, v125
	v_mfma_f32_32x32x16_bf16 v[80:95], v[196:199], v[152:155], v[80:95]
	v_max3_f32 v0, v0, v126, v127
	ds_bpermute_b32 v4, v213, v0
	s_waitcnt lgkmcnt(0)
	v_max_f32_e32 v4, v4, v4
	v_mfma_f32_32x32x16_bf16 v[80:95], v[200:203], v[156:159], v[80:95]
	v_max_f32_e32 v0, v0, v4
	v_sub_f32_e32 v4, v0, v1
	v_mul_f32_e32 v4, 0x3e38aa3b, v4
	v_cmp_lt_f32_e32 vcc, s7, v4
	s_cbranch_vccz .LBB0_844
	v_max_f32_e32 v0, v0, v0
	v_max_f32_e32 v4, v1, v1
	v_max_f32_e32 v4, v4, v0
	v_sub_f32_e32 v0, v1, v4
	v_mul_f32_e32 v0, 0x3e38aa3b, v0
	v_exp_f32_e32 v0, v0
	s_nop 0
	v_mul_f32_e32 v207, v207, v0
	v_pk_mul_f32 v[78:79], v[78:79], v[0:1] op_sel_hi:[1,0]
	v_pk_mul_f32 v[76:77], v[76:77], v[0:1] op_sel_hi:[1,0]
	v_pk_mul_f32 v[74:75], v[74:75], v[0:1] op_sel_hi:[1,0]
	v_pk_mul_f32 v[72:73], v[72:73], v[0:1] op_sel_hi:[1,0]
	v_pk_mul_f32 v[70:71], v[70:71], v[0:1] op_sel_hi:[1,0]
	v_pk_mul_f32 v[68:69], v[68:69], v[0:1] op_sel_hi:[1,0]
	v_pk_mul_f32 v[66:67], v[66:67], v[0:1] op_sel_hi:[1,0]
	v_pk_mul_f32 v[64:65], v[64:65], v[0:1] op_sel_hi:[1,0]
	v_pk_mul_f32 v[62:63], v[62:63], v[0:1] op_sel_hi:[1,0]
	v_pk_mul_f32 v[60:61], v[60:61], v[0:1] op_sel_hi:[1,0]
	v_pk_mul_f32 v[58:59], v[58:59], v[0:1] op_sel_hi:[1,0]
	v_pk_mul_f32 v[56:57], v[56:57], v[0:1] op_sel_hi:[1,0]
	v_pk_mul_f32 v[54:55], v[54:55], v[0:1] op_sel_hi:[1,0]
	v_pk_mul_f32 v[52:53], v[52:53], v[0:1] op_sel_hi:[1,0]
	v_pk_mul_f32 v[50:51], v[50:51], v[0:1] op_sel_hi:[1,0]
	v_pk_mul_f32 v[48:49], v[48:49], v[0:1] op_sel_hi:[1,0]
	v_mov_b32_e32 v1, v4
.LBB0_844:
	s_mov_b32 s7, 0xf149f2ca
	v_max3_f32 v0, v96, s7, v97
	v_max3_f32 v0, v0, v98, v99
	v_max3_f32 v0, v0, v100, v101
	v_max3_f32 v0, v0, v102, v103
	v_max3_f32 v0, v0, v104, v105
	v_max3_f32 v0, v0, v106, v107
	v_max3_f32 v0, v0, v108, v109
	v_max3_f32 v0, v0, v110, v111
	v_max3_f32 v0, v0, v80, v81
	v_max3_f32 v0, v0, v82, v83
	v_max3_f32 v0, v0, v84, v85
	v_max3_f32 v0, v0, v86, v87
	v_max3_f32 v0, v0, v88, v89
	v_max3_f32 v0, v0, v90, v91
	v_max3_f32 v0, v0, v92, v93
	v_max3_f32 v0, v0, v94, v95
	ds_bpermute_b32 v4, v213, v0
	s_mov_b32 s7, 0x41000000
	s_waitcnt lgkmcnt(0)
	v_max_f32_e32 v4, v4, v4
	v_max_f32_e32 v0, v0, v4
	v_sub_f32_e32 v4, v0, v191
	v_mul_f32_e32 v4, 0x3e38aa3b, v4
	v_cmp_lt_f32_e32 vcc, s7, v4
	s_cbranch_vccz .LBB0_835
	v_max_f32_e32 v0, v0, v0
	v_max_f32_e32 v4, v191, v191
	v_max_f32_e32 v4, v4, v0
	v_sub_f32_e32 v0, v191, v4
	v_mul_f32_e32 v0, 0x3e38aa3b, v0
	v_exp_f32_e32 v0, v0
	v_mov_b32_e32 v191, v4
	v_mul_f32_e32 v206, v206, v0
	v_pk_mul_f32 v[46:47], v[46:47], v[0:1] op_sel_hi:[1,0]
	v_pk_mul_f32 v[44:45], v[44:45], v[0:1] op_sel_hi:[1,0]
	v_pk_mul_f32 v[42:43], v[42:43], v[0:1] op_sel_hi:[1,0]
	v_pk_mul_f32 v[40:41], v[40:41], v[0:1] op_sel_hi:[1,0]
	v_pk_mul_f32 v[38:39], v[38:39], v[0:1] op_sel_hi:[1,0]
	v_pk_mul_f32 v[36:37], v[36:37], v[0:1] op_sel_hi:[1,0]
	v_pk_mul_f32 v[34:35], v[34:35], v[0:1] op_sel_hi:[1,0]
	v_pk_mul_f32 v[32:33], v[32:33], v[0:1] op_sel_hi:[1,0]
	v_pk_mul_f32 v[30:31], v[30:31], v[0:1] op_sel_hi:[1,0]
	v_pk_mul_f32 v[28:29], v[28:29], v[0:1] op_sel_hi:[1,0]
	v_pk_mul_f32 v[26:27], v[26:27], v[0:1] op_sel_hi:[1,0]
	v_pk_mul_f32 v[24:25], v[24:25], v[0:1] op_sel_hi:[1,0]
	v_pk_mul_f32 v[22:23], v[22:23], v[0:1] op_sel_hi:[1,0]
	v_pk_mul_f32 v[20:21], v[20:21], v[0:1] op_sel_hi:[1,0]
	v_pk_mul_f32 v[18:19], v[18:19], v[0:1] op_sel_hi:[1,0]
	v_pk_mul_f32 v[16:17], v[16:17], v[0:1] op_sel_hi:[1,0]
	s_branch .LBB0_835
; #define MFMA32(a, b, c) __builtin_amdgcn_mfma_f32_32x32x16_bf16((a), (b), (c), 0, 0, 0)
; DI int crow(int i, int h) { return (i & 3) + 8 * (i >> 2) + 4 * h; }
; DI float fexp2(float x) { return __builtin_amdgcn_exp2f(x); }
; template <int DK, int DV, int MODE, int QB, bool PACK = false>
; DI void attn_item(const AttArgs& a, int q0, int t_lo, int t_hi) {
;     ...
;       f32x16 s[QB][2];
; #pragma unroll
;       for (int qb = 0; qb < QB; ++qb)
; #pragma unroll
;         for (int kb = 0; kb < 2; ++kb) {
; #pragma unroll
;           for (int i = 0; i < 16; ++i) s[qb][kb][i] = 0.f;
;           const unsigned char* kp = Kb + (kb * 32 + r) * KST + h * 16;
; #pragma unroll
;           for (int st = 0; st < NKS; ++st) {
;             const bf16x8 kf = *(const bf16x8*)(kp + st * 32);
;             s[qb][kb] = MFMA32(kf, qf[qb][st], s[qb][kb]);
;           }
;         }
; #pragma unroll
;       for (int qb = 0; qb < QB; ++qb) {
;         const int qidx = wq0 + qb * 32 + r;
;         float mloc = -1e30f;
; #pragma unroll
;         for (int kb = 0; kb < 2; ++kb)
; #pragma unroll
;           for (int i = 0; i < 16; ++i) {
;             float tt = s[qb][kb][i];
;             if constexpr (MODE == 1) {
;               const int kidx = tile * 64 + kb * 32 + crow(i, h);
;               const int d = kidx - qidx;
;               tt = (d <= 128 && d >= -128) ? tt : -1e30f;
;               s[qb][kb][i] = tt;
;             }
;             if constexpr (MODE == 2) {
;               const int kc = kb * 32 + crow(i, h);
;               const bool ok = (kc >= c0[qb]) && (kc < c0[qb] + 16);
;               const int bi = ok ? ((tile - rq + 7) * 31 + kc - cq[qb] + 15) : 0;
;               tt = ok ? fmaf(tt, scale, rpbs[bi]) : -1e30f;
;               s[qb][kb][i] = tt;
;             }
;             mloc = fmaxf(mloc, tt);
;           }
;         mloc = fmaxf(mloc, __shfl_xor(mloc, 32));
;         if (__any((mloc - m[qb]) * cexp > 8.f)) {
;           const float mnew = fmaxf(m[qb], mloc);
;           const float alpha = fexp2((m[qb] - mnew) * cexp);
;           m[qb] = mnew;
;           lsum[qb] *= alpha;
; #pragma unroll
;           for (int d = 0; d < NDB; ++d)
; #pragma unroll
;             for (int i = 0; i < 16; ++i) o[qb][d][i] *= alpha;
;         }
.LBB0_846:
	v_add_u32_e32 v96, v188, v208
	ds_read_b128 v[4:7], v96 offset:23136
	ds_read_b128 v[8:11], v96 offset:23104
	ds_read_b128 v[12:15], v96 offset:23072
	ds_read_b128 v[80:83], v96 offset:23040
	ds_read_b128 v[84:87], v96 offset:18528
	ds_read_b128 v[88:91], v96 offset:18496
	ds_read_b128 v[92:95], v96 offset:18432
	s_waitcnt vmcnt(1)
	ds_read_b128 v[176:179], v96 offset:18464
	s_waitcnt lgkmcnt(4)
	v_mfma_f32_32x32x16_bf16 v[112:127], v[80:83], v[172:175], 0
	s_mov_b32 s2, 0xf149f2ca
	s_waitcnt lgkmcnt(1)
	v_mfma_f32_32x32x16_bf16 v[128:143], v[92:95], v[172:175], 0
	v_mfma_f32_32x32x16_bf16 v[96:111], v[92:95], v[144:147], 0
	s_waitcnt lgkmcnt(0)
	v_mfma_f32_32x32x16_bf16 v[128:143], v[176:179], v[168:171], v[128:143]
	v_mfma_f32_32x32x16_bf16 v[96:111], v[176:179], v[148:151], v[96:111]
	v_mfma_f32_32x32x16_bf16 v[128:143], v[88:91], v[164:167], v[128:143]
	v_mfma_f32_32x32x16_bf16 v[96:111], v[88:91], v[152:155], v[96:111]
	v_mfma_f32_32x32x16_bf16 v[128:143], v[84:87], v[160:163], v[128:143]
	v_mfma_f32_32x32x16_bf16 v[96:111], v[84:87], v[156:159], v[96:111]
	v_mfma_f32_32x32x16_bf16 v[80:95], v[80:83], v[144:147], 0
	v_mfma_f32_32x32x16_bf16 v[112:127], v[12:15], v[168:171], v[112:127]
	v_mfma_f32_32x32x16_bf16 v[80:95], v[12:15], v[148:151], v[80:95]
	v_mfma_f32_32x32x16_bf16 v[112:127], v[8:11], v[164:167], v[112:127]
	v_mfma_f32_32x32x16_bf16 v[80:95], v[8:11], v[152:155], v[80:95]
	v_mfma_f32_32x32x16_bf16 v[112:127], v[4:7], v[160:163], v[112:127]
	v_mfma_f32_32x32x16_bf16 v[80:95], v[4:7], v[156:159], v[80:95]
	s_nop 3
	v_max3_f32 v4, v128, s2, v129
	v_max3_f32 v4, v4, v130, v131
	v_max3_f32 v4, v4, v132, v133
	v_max3_f32 v4, v4, v134, v135
	v_max3_f32 v4, v4, v136, v137
	v_max3_f32 v4, v4, v138, v139
	v_max3_f32 v4, v4, v140, v141
	v_max3_f32 v4, v4, v142, v143
	v_max3_f32 v4, v4, v112, v113
	v_max3_f32 v4, v4, v114, v115
	v_max3_f32 v4, v4, v116, v117
	v_max3_f32 v4, v4, v118, v119
	v_max3_f32 v4, v4, v120, v121
	v_max3_f32 v4, v4, v122, v123
	v_max3_f32 v4, v4, v124, v125
	v_max3_f32 v4, v4, v126, v127
	ds_bpermute_b32 v5, v213, v4
	s_mov_b32 s2, 0x41000000
	s_waitcnt lgkmcnt(0)
	v_max_f32_e32 v5, v5, v5
	v_max_f32_e32 v4, v4, v5
	v_sub_f32_e32 v5, v4, v1
	v_mul_f32_e32 v5, 0x3e38aa3b, v5
	v_cmp_lt_f32_e32 vcc, s2, v5
	s_cbranch_vccz .LBB0_848
	v_max_f32_e32 v0, v4, v4
	v_max_f32_e32 v4, v1, v1
	v_max_f32_e32 v4, v4, v0
	v_sub_f32_e32 v0, v1, v4
	v_mul_f32_e32 v0, 0x3e38aa3b, v0
	v_exp_f32_e32 v0, v0
	s_nop 0
	v_mul_f32_e32 v207, v207, v0
	v_pk_mul_f32 v[78:79], v[78:79], v[0:1] op_sel_hi:[1,0]
	v_pk_mul_f32 v[76:77], v[76:77], v[0:1] op_sel_hi:[1,0]
	v_pk_mul_f32 v[74:75], v[74:75], v[0:1] op_sel_hi:[1,0]
	v_pk_mul_f32 v[72:73], v[72:73], v[0:1] op_sel_hi:[1,0]
	v_pk_mul_f32 v[70:71], v[70:71], v[0:1] op_sel_hi:[1,0]
	v_pk_mul_f32 v[68:69], v[68:69], v[0:1] op_sel_hi:[1,0]
	v_pk_mul_f32 v[66:67], v[66:67], v[0:1] op_sel_hi:[1,0]
	v_pk_mul_f32 v[64:65], v[64:65], v[0:1] op_sel_hi:[1,0]
	v_pk_mul_f32 v[62:63], v[62:63], v[0:1] op_sel_hi:[1,0]
	v_pk_mul_f32 v[60:61], v[60:61], v[0:1] op_sel_hi:[1,0]
	v_pk_mul_f32 v[58:59], v[58:59], v[0:1] op_sel_hi:[1,0]
	v_pk_mul_f32 v[56:57], v[56:57], v[0:1] op_sel_hi:[1,0]
	v_pk_mul_f32 v[54:55], v[54:55], v[0:1] op_sel_hi:[1,0]
	v_pk_mul_f32 v[52:53], v[52:53], v[0:1] op_sel_hi:[1,0]
	v_pk_mul_f32 v[50:51], v[50:51], v[0:1] op_sel_hi:[1,0]
	v_pk_mul_f32 v[48:49], v[48:49], v[0:1] op_sel_hi:[1,0]
	v_mul_f32_e32 v0, 0xbe38aa3b, v4
.LBB0_848:
	s_mov_b32 s2, 0xf149f2ca
	v_max3_f32 v1, v96, s2, v97
	v_max3_f32 v1, v1, v98, v99
	v_max3_f32 v1, v1, v100, v101
	v_max3_f32 v1, v1, v102, v103
	v_max3_f32 v1, v1, v104, v105
	v_max3_f32 v1, v1, v106, v107
	v_max3_f32 v1, v1, v108, v109
	v_max3_f32 v1, v1, v110, v111
	v_max3_f32 v1, v1, v80, v81
	v_max3_f32 v1, v1, v82, v83
	v_max3_f32 v1, v1, v84, v85
	v_max3_f32 v1, v1, v86, v87
	v_max3_f32 v1, v1, v88, v89
	v_max3_f32 v1, v1, v90, v91
	v_max3_f32 v1, v1, v92, v93
	v_max3_f32 v1, v1, v94, v95
	ds_bpermute_b32 v4, v213, v1
	s_mov_b32 s2, 0x41000000
	s_waitcnt lgkmcnt(0)
	v_max_f32_e32 v4, v4, v4
	v_max_f32_e32 v1, v1, v4
	v_sub_f32_e32 v4, v1, v191
	v_mul_f32_e32 v4, 0x3e38aa3b, v4
	v_cmp_lt_f32_e32 vcc, s2, v4
	s_cbranch_vccz .LBB0_633
	v_max_f32_e32 v1, v1, v1
	v_max_f32_e32 v4, v191, v191
	v_max_f32_e32 v1, v4, v1
	v_sub_f32_e32 v4, v191, v1
	v_mul_f32_e32 v4, 0x3e38aa3b, v4
	v_exp_f32_e32 v4, v4
	v_mul_f32_e32 v190, 0xbe38aa3b, v1
	v_mul_f32_e32 v206, v206, v4
	v_pk_mul_f32 v[46:47], v[46:47], v[4:5] op_sel_hi:[1,0]
	v_pk_mul_f32 v[44:45], v[44:45], v[4:5] op_sel_hi:[1,0]
	v_pk_mul_f32 v[42:43], v[42:43], v[4:5] op_sel_hi:[1,0]
	v_pk_mul_f32 v[40:41], v[40:41], v[4:5] op_sel_hi:[1,0]
	v_pk_mul_f32 v[38:39], v[38:39], v[4:5] op_sel_hi:[1,0]
	v_pk_mul_f32 v[36:37], v[36:37], v[4:5] op_sel_hi:[1,0]
	v_pk_mul_f32 v[34:35], v[34:35], v[4:5] op_sel_hi:[1,0]
	v_pk_mul_f32 v[32:33], v[32:33], v[4:5] op_sel_hi:[1,0]
	v_pk_mul_f32 v[30:31], v[30:31], v[4:5] op_sel_hi:[1,0]
	v_pk_mul_f32 v[28:29], v[28:29], v[4:5] op_sel_hi:[1,0]
	v_pk_mul_f32 v[26:27], v[26:27], v[4:5] op_sel_hi:[1,0]
	v_pk_mul_f32 v[24:25], v[24:25], v[4:5] op_sel_hi:[1,0]
	v_pk_mul_f32 v[22:23], v[22:23], v[4:5] op_sel_hi:[1,0]
	v_pk_mul_f32 v[20:21], v[20:21], v[4:5] op_sel_hi:[1,0]
	v_pk_mul_f32 v[18:19], v[18:19], v[4:5] op_sel_hi:[1,0]
	v_pk_mul_f32 v[16:17], v[16:17], v[4:5] op_sel_hi:[1,0]
	s_branch .LBB0_633
